# attention main loop: waves 4-7 no longer issue their duplicate K-rope LDS-DMA (waves 0-3 load all four pieces); their step-top wait is vmcnt(2)
# speedup vs baseline: 1.0078x; 1.0078x over previous
; #define AT_WAIT_BAR(N) asm volatile("s_waitcnt vmcnt(" #N ") lgkmcnt(0)\n\ts_barrier" ::: "memory")
; template <int THRL>
; __device__ __forceinline__ void attn_item(int b, int h, int s, const bf16_t* Q, const bf16_t* KN, const bf16_t* KR, const bf16_t* V, const float* goa  , bf16_t* Y, float* ssqy, AT_LAS char* shm, int wid0) {
;     ...
;         for (int t = 0; t < NT; ++t) {
;             AT_WAIT_BAR(3);
;             AT_DMA(t + 3, t + 2, NT);
.LBB13_765:
	s_min_u32 s84, s9, s5
	s_add_i32 s88, s9, -1
	s_min_u32 s92, s88, s5
	s_and_b32 s88, s84, 3
	s_and_b64 vcc, exec, s[0:1]
	s_cbranch_vccnz .Lat0_lw
	s_waitcnt vmcnt(3) lgkmcnt(0)
	s_branch .Lat0_lwd
.Lat0_lw:
	s_waitcnt vmcnt(2) lgkmcnt(0)
.Lat0_lwd:
	s_barrier
	s_lshl_b64 vcc, s[84:85], 16
	s_mulk_i32 s88, 0x3000
	v_lshl_add_u64 v[154:155], v[122:123], 0, vcc
	s_add_i32 s89, s88, s33
	s_mov_b32 s93, m0
	s_mov_b32 m0, s89
	s_nop 0
	global_load_lds_dwordx4 v[154:155], off
	s_mov_b32 m0, s93
	s_lshl_b64 vcc, s[84:85], 12
	s_add_i32 s84, s88, s78
	v_lshl_add_u64 v[154:155], v[124:125], 0, vcc
	s_and_b64 vcc, exec, s[0:1]
	s_cbranch_vccnz .Lat0_rope_skip
	s_mov_b32 s88, m0
	s_mov_b32 m0, s84
	s_nop 0
	global_load_lds_dwordx4 v[154:155], off
	s_mov_b32 m0, s88
.Lat0_rope_skip:
	s_lshl_b32 s84, s92, 13
	s_mov_b32 s93, s85
	s_and_b32 s84, s84, 0x6000
	s_lshl_b64 vcc, s[92:93], 16
	s_add_i32 s84, s84, s87
	v_lshl_add_u64 v[154:155], v[126:127], 0, vcc
	s_mov_b32 s88, m0
	s_mov_b32 m0, s84
	s_nop 0
	global_load_lds_dwordx4 v[154:155], off
	s_mov_b32 m0, s88
	s_add_i32 s84, s81, s9
	s_add_i32 s84, s84, -3
	s_cmp_le_i32 s84, s2
	s_cselect_b64 s[92:93], -1, 0
	s_andn2_b64 vcc, exec, s[0:1]
	s_cbranch_vccz .LBB13_768
	s_andn2_b64 vcc, exec, s[92:93]
	s_cbranch_vccz .Lat0_e_need

; #define AT_WAIT_BAR(N) asm volatile("s_waitcnt vmcnt(" #N ") lgkmcnt(0)\n\ts_barrier" ::: "memory")
; template <int THRL>
; __device__ __forceinline__ void attn_item(int b, int h, int s, const bf16_t* Q, const bf16_t* KN, const bf16_t* KR, const bf16_t* V, const float* goa  , bf16_t* Y, float* ssqy, AT_LAS char* shm, int wid0) {
;     ...
;         for (int t = 0; t < NT; ++t) {
;             AT_WAIT_BAR(3);
;             AT_DMA(t + 3, t + 2, NT);
.LBB13_1743:
	s_min_u32 s84, s80, s5
	s_add_i32 s88, s80, -1
	s_min_u32 s92, s88, s5
	s_and_b32 s88, s84, 3
	s_and_b64 vcc, exec, s[90:91]
	s_cbranch_vccnz .Lat1_lw
	s_waitcnt vmcnt(3) lgkmcnt(0)
	s_branch .Lat1_lwd

; template <int THRL>
; __device__ __forceinline__ void attn_item(int b, int h, int s, const bf16_t* Q, const bf16_t* KN, const bf16_t* KR, const bf16_t* V, const float* goa  , bf16_t* Y, float* ssqy, AT_LAS char* shm, int wid0) {
;     ...
;             const int jb = t - (NT - 4);
;             const bool need = jb <= wq;
.Lat1_lwd:
	s_barrier
	s_lshl_b64 vcc, s[84:85], 16
	s_mulk_i32 s88, 0x3000
	v_lshl_add_u64 v[154:155], v[122:123], 0, vcc
	s_add_i32 s89, s88, s87
	s_mov_b32 s93, m0
	s_mov_b32 m0, s89
	s_nop 0
	global_load_lds_dwordx4 v[154:155], off
	s_mov_b32 m0, s93
	s_lshl_b64 vcc, s[84:85], 12
	s_add_i32 s84, s88, s2
	v_lshl_add_u64 v[154:155], v[124:125], 0, vcc
	s_and_b64 vcc, exec, s[90:91]
	s_cbranch_vccnz .Lat1_rope_skip
	s_mov_b32 s88, m0
	s_mov_b32 m0, s84
	s_nop 0
	global_load_lds_dwordx4 v[154:155], off
	s_mov_b32 m0, s88
.Lat1_rope_skip:
	s_lshl_b32 s84, s92, 13
	s_mov_b32 s93, s85
	s_and_b32 s84, s84, 0x6000
	s_lshl_b64 vcc, s[92:93], 16
	s_add_i32 s84, s84, s78
	v_lshl_add_u64 v[154:155], v[126:127], 0, vcc
	s_mov_b32 s88, m0
	s_mov_b32 m0, s84
	s_nop 0
	global_load_lds_dwordx4 v[154:155], off
	s_mov_b32 m0, s88
	s_add_i32 s84, s81, s80
	s_add_i32 s84, s84, -3
	s_cmp_le_i32 s84, s33
	s_cselect_b64 s[92:93], -1, 0
	s_andn2_b64 vcc, exec, s[90:91]
	s_cbranch_vccz .LBB13_1746
	s_andn2_b64 vcc, exec, s[92:93]
	s_cbranch_vccz .Lat1_e_need
